# prep phase: non-temporal (nt) hint on the 128-bit streaming stores of the RWKV/GDN operand arrays (written once, read by the scan phase), on top of the v86 combination
# speedup vs baseline: 1.0097x; 1.0005x over previous
.LBB0_1809:
	s_or_b64 exec, exec, s[2:3]
	s_waitcnt vmcnt(3)
	v_lshlrev_b32_e32 v110, 16, v100
	v_and_b32_e32 v111, 0xffff0000, v100
	v_lshlrev_b32_e32 v112, 16, v101
	v_and_b32_e32 v113, 0xffff0000, v101
	v_lshlrev_b32_e32 v124, 16, v76
	v_and_b32_e32 v125, 0xffff0000, v76
	v_lshlrev_b32_e32 v126, 16, v77
	v_and_b32_e32 v127, 0xffff0000, v77
	v_lshlrev_b32_e32 v134, 16, v74
	v_and_b32_e32 v135, 0xffff0000, v74
	v_lshlrev_b32_e32 v136, 16, v75
	v_and_b32_e32 v137, 0xffff0000, v75
	v_lshlrev_b32_e32 v140, 16, v44
	v_and_b32_e32 v141, 0xffff0000, v44
	v_lshlrev_b32_e32 v142, 16, v45
	v_and_b32_e32 v143, 0xffff0000, v45
	v_lshlrev_b32_e32 v152, 16, v42
	v_and_b32_e32 v153, 0xffff0000, v42
	v_lshlrev_b32_e32 v154, 16, v43
	v_and_b32_e32 v155, 0xffff0000, v43
	v_lshlrev_b32_e32 v144, 16, v40
	v_and_b32_e32 v145, 0xffff0000, v40
	v_lshlrev_b32_e32 v146, 16, v41
	v_and_b32_e32 v147, 0xffff0000, v41
	v_lshlrev_b64 v[100:101], 10, v[38:39]
	global_load_dwordx4 v[38:41], v50, s[34:35]
	global_load_dwordx4 v[178:181], v50, s[76:77]
	global_load_dwordx4 v[42:45], v50, s[78:79]
	global_load_dwordx4 v[74:77], v50, s[36:37]
	global_load_dwordx4 v[62:65], v50, s[40:41]
	global_load_dwordx4 v[182:185], v50, s[42:43]
	global_load_dwordx4 v[66:69], v50, s[52:53]
	v_sub_f32_e32 v149, v55, v145
	v_sub_f32_e32 v148, v54, v144
	v_sub_f32_e32 v55, v59, v153
	v_sub_f32_e32 v54, v58, v152
	v_sub_f32_e32 v151, v57, v147
	v_sub_f32_e32 v150, v56, v146
	v_sub_f32_e32 v57, v61, v155
	v_sub_f32_e32 v56, v60, v154
	v_lshlrev_b32_e32 v120, 16, v80
	v_and_b32_e32 v121, 0xffff0000, v80
	v_lshlrev_b32_e32 v122, 16, v81
	v_and_b32_e32 v123, 0xffff0000, v81
	v_lshlrev_b32_e32 v114, 16, v78
	v_and_b32_e32 v115, 0xffff0000, v78
	v_lshlrev_b32_e32 v116, 16, v79
	v_and_b32_e32 v117, 0xffff0000, v79
	v_lshlrev_b32_e32 v128, 16, v72
	v_and_b32_e32 v129, 0xffff0000, v72
	v_lshlrev_b32_e32 v130, 16, v73
	v_and_b32_e32 v131, 0xffff0000, v73
	ds_read_b128 v[78:81], v168 offset:16896
	ds_read_b128 v[70:73], v168 offset:25600
	ds_read_b128 v[50:53], v168 offset:34304
	v_sub_f32_e32 v61, v49, v143
	v_sub_f32_e32 v60, v48, v142
	v_sub_f32_e32 v59, v47, v141
	v_sub_f32_e32 v58, v46, v140
	v_sub_f32_e32 v31, v31, v135
	v_sub_f32_e32 v30, v30, v134
	v_sub_f32_e32 v33, v33, v137
	v_sub_f32_e32 v32, v32, v136
	v_sub_f32_e32 v35, v35, v129
	v_sub_f32_e32 v34, v34, v128
	v_sub_f32_e32 v37, v37, v131
	v_sub_f32_e32 v36, v36, v130
	v_sub_f32_e32 v19, v19, v121
	v_sub_f32_e32 v18, v18, v120
	v_sub_f32_e32 v21, v21, v123
	v_sub_f32_e32 v20, v20, v122
	v_sub_f32_e32 v23, v23, v115
	v_sub_f32_e32 v22, v22, v114
	v_sub_f32_e32 v25, v25, v117
	v_sub_f32_e32 v24, v24, v116
	s_waitcnt vmcnt(8)
	v_lshlrev_b32_e32 v106, 16, v96
	v_and_b32_e32 v107, 0xffff0000, v96
	v_lshlrev_b32_e32 v108, 16, v97
	v_and_b32_e32 v109, 0xffff0000, v97
	v_lshlrev_b32_e32 v96, 16, v98
	v_and_b32_e32 v97, 0xffff0000, v98
	v_lshlrev_b32_e32 v98, 16, v99
	v_and_b32_e32 v99, 0xffff0000, v99
	s_waitcnt vmcnt(7)
	v_lshlrev_b32_e32 v92, 16, v94
	v_and_b32_e32 v93, 0xffff0000, v94
	v_lshlrev_b32_e32 v94, 16, v95
	v_and_b32_e32 v95, 0xffff0000, v95
	s_add_i32 s4, s4, s58
	s_add_i32 s1, s1, s50
	s_waitcnt vmcnt(6)
	v_pk_fma_f32 v[40:41], v[40:41], v[150:151], v[146:147]
	s_waitcnt vmcnt(5)
	v_pk_fma_f32 v[152:153], v[54:55], v[178:179], v[152:153]
	v_pk_fma_f32 v[56:57], v[56:57], v[180:181], v[154:155]
	s_waitcnt vmcnt(4)
	v_pk_fma_f32 v[42:43], v[58:59], v[42:43], v[140:141]
	v_or_b32_e32 v58, v100, v176
	s_waitcnt vmcnt(1)
	v_pk_mul_f32 v[48:49], v[152:153], v[182:183]
	v_pk_mul_f32 v[154:155], v[56:57], v[184:185]
	v_pk_mul_f32 v[46:47], v[48:49], v[48:49]
	v_mov_b32_e32 v59, v101
	v_pk_fma_f32 v[46:47], v[154:155], v[154:155], v[46:47]
	v_lshlrev_b64 v[58:59], 2, v[58:59]
	v_add_f32_e32 v0, v46, v47
	s_waitcnt lgkmcnt(2)
	v_add_f32_e32 v46, v74, v78
	v_max_f32_e64 v47, -v46, 0
	v_mul_f32_e64 v46, |v46|, s81
	v_exp_f32_e32 v46, v46
	v_add_f32_dpp v0, v0, v0 quad_perm:[1,0,3,2] row_mask:0xf bank_mask:0xf bound_ctrl:1
	v_pk_fma_f32 v[38:39], v[38:39], v[148:149], v[144:145]
	v_pk_fma_f32 v[44:45], v[60:61], v[44:45], v[142:143]
	v_add_f32_e32 v46, 1.0, v46
	v_cmp_gt_f32_e64 s[2:3], s82, v46
	v_add_f32_dpp v0, v0, v0 quad_perm:[2,3,0,1] row_mask:0xf bank_mask:0xf bound_ctrl:1
	v_lshl_add_u64 v[60:61], s[54:55], 0, v[58:59]
	v_cndmask_b32_e64 v54, 0, 32, s[2:3]
	v_ldexp_f32 v46, v46, v54
	v_log_f32_e32 v46, v46
	v_add_f32_dpp v0, v0, v0 row_half_mirror row_mask:0xf bank_mask:0xf bound_ctrl:1
	global_store_dwordx4 v[60:61], v[38:41], off nt
	v_mul_f32_e32 v54, 0x3f317217, v46
	v_fma_f32 v54, v46, s83, -v54
	v_fmac_f32_e32 v54, 0x3377d1cf, v46
	v_fmac_f32_e32 v54, 0x3f317217, v46
	v_cmp_lt_f32_e64 s[12:13], |v46|, s84
	v_add_f32_dpp v0, v0, v0 row_ror:8 row_mask:0xf bank_mask:0xf bound_ctrl:1
	v_add_f32_e32 v0, 0x2b8cbccc, v0
	v_cndmask_b32_e64 v46, v46, v54, s[12:13]
	v_cndmask_b32_e64 v54, 0, v218, s[2:3]
	v_sub_f32_e32 v46, v46, v54
	v_add_f32_e32 v46, v47, v46
	s_waitcnt lgkmcnt(1)
	v_add_f32_e32 v47, v62, v70
	v_mul_f32_e32 v47, 0xbfb8aa3b, v47
	v_exp_f32_e32 v47, v47
	v_rsq_f32_e32 v0, v0
	v_sub_f32_e32 v46, -0.5, v46
	v_mul_f32_e32 v46, 0x3fb8aa3b, v46
	v_add_f32_e32 v47, 1.0, v47
	v_rcp_f32_e32 v62, v47
	v_add_f32_e32 v47, v75, v79
	v_max_f32_e64 v54, -v47, 0
	v_mul_f32_e64 v47, |v47|, s81
	v_exp_f32_e32 v47, v47
	v_exp_f32_e32 v46, v46
	v_lshl_add_u64 v[38:39], s[56:57], 0, v[58:59]
	v_add_f32_e32 v47, 1.0, v47
	v_cmp_gt_f32_e64 s[2:3], s82, v47
	v_mul_f32_e32 v46, 0xbfb8aa3b, v46
	v_exp_f32_e32 v46, v46
	v_cndmask_b32_e64 v55, 0, 32, s[2:3]
	v_ldexp_f32 v47, v47, v55
	v_log_f32_e32 v47, v47
	s_nop 0
	v_mul_f32_e32 v55, 0x3f317217, v47
	v_fma_f32 v55, v47, s83, -v55
	v_fmac_f32_e32 v55, 0x3377d1cf, v47
	v_fmac_f32_e32 v55, 0x3f317217, v47
	v_cmp_lt_f32_e64 s[12:13], |v47|, s84
	s_nop 1
	v_cndmask_b32_e64 v47, v47, v55, s[12:13]
	v_cndmask_b32_e64 v55, 0, v218, s[2:3]
	v_sub_f32_e32 v47, v47, v55
	v_add_f32_e32 v47, v54, v47
	v_add_f32_e32 v54, v63, v71
	v_pk_mul_f32 v[70:71], v[48:49], v[0:1] op_sel_hi:[1,0]
	v_add_f32_e32 v48, v76, v80
	v_max_f32_e64 v49, -v48, 0
	v_mul_f32_e64 v48, |v48|, s81
	v_exp_f32_e32 v48, v48
	v_mul_f32_e32 v54, 0xbfb8aa3b, v54
	v_sub_f32_e32 v47, -0.5, v47
	v_exp_f32_e32 v54, v54
	v_add_f32_e32 v48, 1.0, v48
	v_cmp_gt_f32_e64 s[2:3], s82, v48
	v_mul_f32_e32 v47, 0x3fb8aa3b, v47
	v_exp_f32_e32 v47, v47
	v_cndmask_b32_e64 v74, 0, 32, s[2:3]
	v_ldexp_f32 v48, v48, v74
	v_log_f32_e32 v48, v48
	v_add_f32_e32 v54, 1.0, v54
	v_rcp_f32_e32 v63, v54
	v_mul_f32_e32 v47, 0xbfb8aa3b, v47
	v_mul_f32_e32 v74, 0x3f317217, v48
	v_fma_f32 v74, v48, s83, -v74
	v_fmac_f32_e32 v74, 0x3377d1cf, v48
	v_fmac_f32_e32 v74, 0x3f317217, v48
	v_cmp_lt_f32_e64 s[12:13], |v48|, s84
	v_exp_f32_e32 v47, v47
	v_xor_b32_e32 v55, 0x80000000, v71
	v_cndmask_b32_e64 v48, v48, v74, s[12:13]
	v_cndmask_b32_e64 v74, 0, v218, s[2:3]
	v_sub_f32_e32 v48, v48, v74
	v_add_f32_e32 v48, v49, v48
	v_add_f32_e32 v49, v64, v72
	v_mul_f32_e32 v49, 0xbfb8aa3b, v49
	v_exp_f32_e32 v49, v49
	v_sub_f32_e32 v48, -0.5, v48
	v_mul_f32_e32 v48, 0x3fb8aa3b, v48
	v_exp_f32_e32 v48, v48
	v_add_f32_e32 v49, 1.0, v49
	v_rcp_f32_e32 v72, v49
	v_add_f32_e32 v49, v77, v81
	v_max_f32_e64 v64, -v49, 0
	v_mul_f32_e64 v49, |v49|, s81
	v_exp_f32_e32 v49, v49
	v_mul_f32_e32 v48, 0xbfb8aa3b, v48
	v_exp_f32_e32 v48, v48
	v_xor_b32_e32 v54, 0x80000000, v70
	v_add_f32_e32 v49, 1.0, v49
	v_cmp_gt_f32_e64 s[2:3], s82, v49
	s_nop 1
	v_cndmask_b32_e64 v74, 0, 32, s[2:3]
	v_ldexp_f32 v49, v49, v74
	v_log_f32_e32 v49, v49
	s_nop 0
	v_mul_f32_e32 v74, 0x3f317217, v49
	v_fma_f32 v74, v49, s83, -v74
	v_fmac_f32_e32 v74, 0x3377d1cf, v49
	v_fmac_f32_e32 v74, 0x3f317217, v49
	v_cmp_lt_f32_e64 s[12:13], |v49|, s84
	s_nop 1
	v_cndmask_b32_e64 v49, v49, v74, s[12:13]
	v_cndmask_b32_e64 v74, 0, v218, s[2:3]
	v_sub_f32_e32 v49, v49, v74
	v_add_f32_e32 v49, v64, v49
	v_add_f32_e32 v64, v65, v73
	v_mul_f32_e32 v64, 0xbfb8aa3b, v64
	v_sub_f32_e32 v49, -0.5, v49
	v_exp_f32_e32 v64, v64
	v_mul_f32_e32 v49, 0x3fb8aa3b, v49
	v_exp_f32_e32 v49, v49
	v_add_f32_e32 v64, 1.0, v64
	v_rcp_f32_e32 v73, v64
	v_mul_f32_e32 v49, 0xbfb8aa3b, v49
	v_exp_f32_e32 v49, v49
	v_pk_add_f32 v[64:65], v[62:63], -1.0 op_sel_hi:[1,0]
	v_pk_add_f32 v[74:75], v[72:73], -1.0 op_sel_hi:[1,0]
	s_waitcnt vmcnt(1)
	v_pk_fma_f32 v[64:65], v[66:67], v[64:65], 1.0 op_sel_hi:[1,1,0]
	v_pk_fma_f32 v[68:69], v[68:69], v[74:75], 1.0 op_sel_hi:[1,1,0]
	v_pk_mul_f32 v[64:65], v[152:153], v[64:65]
	v_pk_mul_f32 v[66:67], v[56:57], v[68:69]
	global_store_dwordx4 v[38:39], v[46:49], off nt
	v_lshl_add_u64 v[38:39], s[66:67], 0, v[58:59]
	v_pk_mul_f32 v[74:75], v[154:155], v[0:1] op_sel_hi:[1,0]
	global_store_dwordx4 v[38:39], v[64:67], off nt
	v_lshl_add_u64 v[38:39], s[68:69], 0, v[58:59]
	v_xor_b32_e32 v56, 0x80000000, v74
	v_xor_b32_e32 v57, 0x80000000, v75
	global_store_dwordx4 v[38:39], v[42:45], off nt
	v_lshl_add_u64 v[38:39], s[70:71], 0, v[58:59]
	v_pk_mul_f32 v[68:69], v[62:63], v[70:71]
	v_pk_mul_f32 v[70:71], v[72:73], v[74:75]
	global_store_dwordx4 v[38:39], v[54:57], off nt
	v_lshl_add_u64 v[38:39], s[72:73], 0, v[58:59]
	global_store_dwordx4 v[38:39], v[68:71], off nt
	v_lshl_add_u64 v[38:39], s[74:75], 0, v[58:59]
	s_waitcnt lgkmcnt(0)
	global_store_dwordx4 v[38:39], v[50:53], off nt
	global_load_dwordx4 v[42:45], v102, s[34:35] offset:256
	global_load_dwordx4 v[70:73], v132, s[76:77]
	s_nop 0
	global_load_dwordx4 v[38:41], v132, s[78:79]
	global_load_dwordx4 v[58:61], v102, s[36:37] offset:256
	global_load_dwordx4 v[50:53], v102, s[40:41] offset:256
	global_load_dwordx4 v[78:81], v102, s[42:43] offset:256
	global_load_dwordx4 v[46:49], v102, s[52:53] offset:256
	ds_read_b128 v[66:69], v168 offset:43008
	ds_read_b128 v[62:65], v168 offset:51712
	ds_read_b128 v[54:57], v168 offset:60416
	s_waitcnt vmcnt(6)
	v_pk_fma_f32 v[34:35], v[34:35], v[42:43], v[128:129]
	s_waitcnt vmcnt(5)
	v_pk_fma_f32 v[74:75], v[30:31], v[70:71], v[134:135]
	v_pk_fma_f32 v[32:33], v[32:33], v[72:73], v[136:137]
	v_sub_f32_e32 v73, v29, v127
	v_sub_f32_e32 v72, v28, v126
	s_waitcnt vmcnt(1)
	v_pk_mul_f32 v[28:29], v[74:75], v[78:79]
	v_sub_f32_e32 v71, v27, v125
	v_sub_f32_e32 v70, v26, v124
	v_pk_mul_f32 v[76:77], v[32:33], v[80:81]
	v_pk_mul_f32 v[26:27], v[28:29], v[28:29]
	s_waitcnt lgkmcnt(1)
	v_add_f32_e32 v53, v53, v65
	v_pk_fma_f32 v[26:27], v[76:77], v[76:77], v[26:27]
	v_mul_f32_e32 v53, 0xbfb8aa3b, v53
	v_add_f32_e32 v0, v26, v27
	v_add_f32_e32 v26, v58, v66
	v_max_f32_e64 v27, -v26, 0
	v_mul_f32_e64 v26, |v26|, s81
	v_exp_f32_e32 v26, v26
	v_add_f32_dpp v0, v0, v0 quad_perm:[1,0,3,2] row_mask:0xf bank_mask:0xf bound_ctrl:1
	v_exp_f32_e32 v53, v53
	v_or_b32_e32 v42, v100, v175
	v_add_f32_e32 v26, 1.0, v26
	v_cmp_gt_f32_e64 s[2:3], s82, v26
	v_add_f32_dpp v0, v0, v0 quad_perm:[2,3,0,1] row_mask:0xf bank_mask:0xf bound_ctrl:1
	v_add_f32_e32 v53, 1.0, v53
	v_cndmask_b32_e64 v30, 0, 32, s[2:3]
	v_ldexp_f32 v26, v26, v30
	v_log_f32_e32 v26, v26
	v_add_f32_dpp v0, v0, v0 row_half_mirror row_mask:0xf bank_mask:0xf bound_ctrl:1
	v_rcp_f32_e32 v53, v53
	v_mov_b32_e32 v43, v101
	v_mul_f32_e32 v30, 0x3f317217, v26
	v_fma_f32 v30, v26, s83, -v30
	v_fmac_f32_e32 v30, 0x3377d1cf, v26
	v_fmac_f32_e32 v30, 0x3f317217, v26
	v_cmp_lt_f32_e64 s[12:13], |v26|, s84
	v_add_f32_dpp v0, v0, v0 row_ror:8 row_mask:0xf bank_mask:0xf bound_ctrl:1
	v_add_f32_e32 v0, 0x2b8cbccc, v0
	v_cndmask_b32_e64 v26, v26, v30, s[12:13]
	v_cndmask_b32_e64 v30, 0, v218, s[2:3]
	v_sub_f32_e32 v26, v26, v30
	v_add_f32_e32 v26, v27, v26
	v_add_f32_e32 v27, v50, v62
	v_mul_f32_e32 v27, 0xbfb8aa3b, v27
	v_exp_f32_e32 v27, v27
	v_rsq_f32_e32 v0, v0
	v_sub_f32_e32 v26, -0.5, v26
	v_mul_f32_e32 v26, 0x3fb8aa3b, v26
	v_add_f32_e32 v27, 1.0, v27
	v_rcp_f32_e32 v50, v27
	v_add_f32_e32 v27, v59, v67
	v_max_f32_e64 v30, -v27, 0
	v_mul_f32_e64 v27, |v27|, s81
	v_exp_f32_e32 v27, v27
	v_pk_mul_f32 v[58:59], v[28:29], v[0:1] op_sel_hi:[1,0]
	v_add_f32_e32 v28, v60, v68
	v_max_f32_e64 v29, -v28, 0
	v_add_f32_e32 v27, 1.0, v27
	v_cmp_gt_f32_e64 s[2:3], s82, v27
	v_mul_f32_e64 v28, |v28|, s81
	v_exp_f32_e32 v28, v28
	v_cndmask_b32_e64 v31, 0, 32, s[2:3]
	v_ldexp_f32 v27, v27, v31
	v_log_f32_e32 v27, v27
	v_add_f32_e32 v28, 1.0, v28
	v_exp_f32_e32 v26, v26
	v_lshlrev_b64 v[42:43], 2, v[42:43]
	v_mul_f32_e32 v31, 0x3f317217, v27
	v_fma_f32 v31, v27, s83, -v31
	v_fmac_f32_e32 v31, 0x3377d1cf, v27
	v_fmac_f32_e32 v31, 0x3f317217, v27
	v_cmp_lt_f32_e64 s[12:13], |v27|, s84
	v_mul_f32_e32 v26, 0xbfb8aa3b, v26
	v_exp_f32_e32 v26, v26
	v_cndmask_b32_e64 v27, v27, v31, s[12:13]
	v_cndmask_b32_e64 v31, 0, v218, s[2:3]
	v_cmp_gt_f32_e64 s[2:3], s82, v28
	v_sub_f32_e32 v27, v27, v31
	v_add_f32_e32 v27, v30, v27
	v_cndmask_b32_e64 v60, 0, 32, s[2:3]
	v_ldexp_f32 v28, v28, v60
	v_log_f32_e32 v28, v28
	v_add_f32_e32 v30, v51, v63
	v_mul_f32_e32 v30, 0xbfb8aa3b, v30
	v_sub_f32_e32 v27, -0.5, v27
	v_mul_f32_e32 v60, 0x3f317217, v28
	v_fma_f32 v60, v28, s83, -v60
	v_fmac_f32_e32 v60, 0x3377d1cf, v28
	v_fmac_f32_e32 v60, 0x3f317217, v28
	v_cmp_lt_f32_e64 s[12:13], |v28|, s84
	v_exp_f32_e32 v30, v30
	v_mul_f32_e32 v27, 0x3fb8aa3b, v27
	v_cndmask_b32_e64 v28, v28, v60, s[12:13]
	v_cndmask_b32_e64 v60, 0, v218, s[2:3]
	v_sub_f32_e32 v28, v28, v60
	v_add_f32_e32 v28, v29, v28
	v_add_f32_e32 v29, v52, v64
	v_mul_f32_e32 v29, 0xbfb8aa3b, v29
	v_exp_f32_e32 v29, v29
	v_sub_f32_e32 v28, -0.5, v28
	v_mul_f32_e32 v28, 0x3fb8aa3b, v28
	v_exp_f32_e32 v27, v27
	v_add_f32_e32 v29, 1.0, v29
	v_rcp_f32_e32 v52, v29
	v_add_f32_e32 v29, v61, v69
	v_max_f32_e64 v60, -v29, 0
	v_mul_f32_e64 v29, |v29|, s81
	v_exp_f32_e32 v29, v29
	v_exp_f32_e32 v28, v28
	v_add_f32_e32 v30, 1.0, v30
	v_rcp_f32_e32 v51, v30
	v_add_f32_e32 v29, 1.0, v29
	v_cmp_gt_f32_e64 s[2:3], s82, v29
	v_mul_f32_e32 v27, 0xbfb8aa3b, v27
	v_mul_f32_e32 v28, 0xbfb8aa3b, v28
	v_cndmask_b32_e64 v61, 0, 32, s[2:3]
	v_ldexp_f32 v29, v29, v61
	v_log_f32_e32 v29, v29
	v_exp_f32_e32 v27, v27
	v_exp_f32_e32 v28, v28
	v_pk_add_f32 v[62:63], v[52:53], -1.0 op_sel_hi:[1,0]
	v_mul_f32_e32 v61, 0x3f317217, v29
	v_fma_f32 v61, v29, s83, -v61
	v_fmac_f32_e32 v61, 0x3377d1cf, v29
	v_fmac_f32_e32 v61, 0x3f317217, v29
	v_cmp_lt_f32_e64 s[12:13], |v29|, s84
	v_pk_fma_f32 v[36:37], v[36:37], v[44:45], v[130:131]
	v_lshl_add_u64 v[44:45], s[54:55], 0, v[42:43]
	v_cndmask_b32_e64 v29, v29, v61, s[12:13]
	v_cndmask_b32_e64 v61, 0, v218, s[2:3]
	v_sub_f32_e32 v29, v29, v61
	v_add_f32_e32 v29, v60, v29
	v_sub_f32_e32 v29, -0.5, v29
	v_mul_f32_e32 v29, 0x3fb8aa3b, v29
	v_exp_f32_e32 v29, v29
	v_pk_add_f32 v[60:61], v[50:51], -1.0 op_sel_hi:[1,0]
	s_waitcnt vmcnt(0)
	v_pk_fma_f32 v[48:49], v[48:49], v[62:63], 1.0 op_sel_hi:[1,1,0]
	v_pk_fma_f32 v[46:47], v[46:47], v[60:61], 1.0 op_sel_hi:[1,1,0]
	v_mul_f32_e32 v29, 0xbfb8aa3b, v29
	v_exp_f32_e32 v29, v29
	global_store_dwordx4 v[44:45], v[34:37], off nt
	v_pk_mul_f32 v[48:49], v[32:33], v[48:49]
	v_pk_mul_f32 v[46:47], v[74:75], v[46:47]
	v_lshl_add_u64 v[34:35], s[56:57], 0, v[42:43]
	global_store_dwordx4 v[34:35], v[26:29], off nt
	v_pk_mul_f32 v[60:61], v[76:77], v[0:1] op_sel_hi:[1,0]
	v_pk_fma_f32 v[40:41], v[72:73], v[40:41], v[126:127]
	v_lshl_add_u64 v[26:27], s[66:67], 0, v[42:43]
	v_pk_fma_f32 v[38:39], v[70:71], v[38:39], v[124:125]
	global_store_dwordx4 v[26:27], v[46:49], off nt
	v_lshl_add_u64 v[26:27], s[68:69], 0, v[42:43]
	v_xor_b32_e32 v31, 0x80000000, v59
	v_xor_b32_e32 v30, 0x80000000, v58
	v_xor_b32_e32 v32, 0x80000000, v60
	v_xor_b32_e32 v33, 0x80000000, v61
	global_store_dwordx4 v[26:27], v[38:41], off nt
	v_lshl_add_u64 v[26:27], s[70:71], 0, v[42:43]
	v_pk_mul_f32 v[50:51], v[50:51], v[58:59]
	v_pk_mul_f32 v[52:53], v[52:53], v[60:61]
	global_store_dwordx4 v[26:27], v[30:33], off nt
	v_lshl_add_u64 v[26:27], s[72:73], 0, v[42:43]
	global_store_dwordx4 v[26:27], v[50:53], off nt
	v_lshl_add_u64 v[26:27], s[74:75], 0, v[42:43]
	s_waitcnt lgkmcnt(0)
	global_store_dwordx4 v[26:27], v[54:57], off nt
	global_load_dwordx4 v[30:33], v102, s[34:35] offset:512
	global_load_dwordx4 v[58:61], v118, s[76:77]
	s_nop 0
	global_load_dwordx4 v[26:29], v118, s[78:79]
	global_load_dwordx4 v[46:49], v102, s[36:37] offset:512
	global_load_dwordx4 v[38:41], v102, s[40:41] offset:512
	global_load_dwordx4 v[66:69], v102, s[42:43] offset:512
	global_load_dwordx4 v[42:45], v102, s[52:53] offset:512
	ds_read_b128 v[54:57], v169 offset:52224
	ds_read_b128 v[50:53], v169 offset:60928
	ds_read_b128 v[34:37], v170
	s_waitcnt vmcnt(6)
	v_pk_fma_f32 v[22:23], v[22:23], v[30:31], v[114:115]
	s_waitcnt vmcnt(5)
	v_pk_fma_f32 v[62:63], v[18:19], v[58:59], v[120:121]
	v_pk_fma_f32 v[20:21], v[20:21], v[60:61], v[122:123]
	v_sub_f32_e32 v61, v17, v113
	v_sub_f32_e32 v60, v16, v112
	s_waitcnt vmcnt(1)
	v_pk_mul_f32 v[16:17], v[62:63], v[66:67]
	v_sub_f32_e32 v59, v15, v111
	v_sub_f32_e32 v58, v14, v110
	v_pk_mul_f32 v[64:65], v[20:21], v[68:69]
	v_pk_mul_f32 v[14:15], v[16:17], v[16:17]
	v_or_b32_e32 v30, v100, v133
	v_pk_fma_f32 v[14:15], v[64:65], v[64:65], v[14:15]
	v_mov_b32_e32 v31, v101
	v_add_f32_e32 v0, v14, v15
	s_waitcnt lgkmcnt(2)
	v_add_f32_e32 v14, v46, v54
	v_max_f32_e64 v15, -v14, 0
	v_mul_f32_e64 v14, |v14|, s81
	v_exp_f32_e32 v14, v14
	v_add_f32_dpp v0, v0, v0 quad_perm:[1,0,3,2] row_mask:0xf bank_mask:0xf bound_ctrl:1
	v_lshlrev_b64 v[30:31], 2, v[30:31]
	v_pk_fma_f32 v[24:25], v[24:25], v[32:33], v[116:117]
	v_add_f32_e32 v14, 1.0, v14
	v_cmp_gt_f32_e64 s[2:3], s82, v14
	v_add_f32_dpp v0, v0, v0 quad_perm:[2,3,0,1] row_mask:0xf bank_mask:0xf bound_ctrl:1
	v_lshl_add_u64 v[32:33], s[54:55], 0, v[30:31]
	v_cndmask_b32_e64 v18, 0, 32, s[2:3]
	v_ldexp_f32 v14, v14, v18
	v_log_f32_e32 v14, v14
	v_add_f32_dpp v0, v0, v0 row_half_mirror row_mask:0xf bank_mask:0xf bound_ctrl:1
	global_store_dwordx4 v[32:33], v[22:25], off nt
	v_pk_fma_f32 v[28:29], v[60:61], v[28:29], v[112:113]
	v_mul_f32_e32 v18, 0x3f317217, v14
	v_fma_f32 v18, v14, s83, -v18
	v_fmac_f32_e32 v18, 0x3377d1cf, v14
	v_fmac_f32_e32 v18, 0x3f317217, v14
	v_cmp_lt_f32_e64 s[12:13], |v14|, s84
	v_add_f32_dpp v0, v0, v0 row_ror:8 row_mask:0xf bank_mask:0xf bound_ctrl:1
	v_add_f32_e32 v0, 0x2b8cbccc, v0
	v_cndmask_b32_e64 v14, v14, v18, s[12:13]
	v_cndmask_b32_e64 v18, 0, v218, s[2:3]
	v_sub_f32_e32 v14, v14, v18
	v_add_f32_e32 v14, v15, v14
	s_waitcnt lgkmcnt(1)
	v_add_f32_e32 v15, v38, v50
	v_mul_f32_e32 v15, 0xbfb8aa3b, v15
	v_exp_f32_e32 v15, v15
	v_rsq_f32_e32 v0, v0
	v_sub_f32_e32 v14, -0.5, v14
	v_mul_f32_e32 v14, 0x3fb8aa3b, v14
	v_add_f32_e32 v15, 1.0, v15
	v_rcp_f32_e32 v38, v15
	v_add_f32_e32 v15, v47, v55
	v_max_f32_e64 v18, -v15, 0
	v_mul_f32_e64 v15, |v15|, s81
	v_exp_f32_e32 v15, v15
	v_pk_mul_f32 v[46:47], v[16:17], v[0:1] op_sel_hi:[1,0]
	v_add_f32_e32 v16, v48, v56
	v_max_f32_e64 v17, -v16, 0
	v_add_f32_e32 v15, 1.0, v15
	v_cmp_gt_f32_e64 s[2:3], s82, v15
	v_mul_f32_e64 v16, |v16|, s81
	v_exp_f32_e32 v16, v16
	v_cndmask_b32_e64 v19, 0, 32, s[2:3]
	v_ldexp_f32 v15, v15, v19
	v_log_f32_e32 v15, v15
	v_add_f32_e32 v16, 1.0, v16
	v_exp_f32_e32 v14, v14
	v_lshl_add_u64 v[22:23], s[56:57], 0, v[30:31]
	v_mul_f32_e32 v19, 0x3f317217, v15
	v_fma_f32 v19, v15, s83, -v19
	v_fmac_f32_e32 v19, 0x3377d1cf, v15
	v_fmac_f32_e32 v19, 0x3f317217, v15
	v_cmp_lt_f32_e64 s[12:13], |v15|, s84
	v_mul_f32_e32 v14, 0xbfb8aa3b, v14
	v_exp_f32_e32 v14, v14
	v_cndmask_b32_e64 v15, v15, v19, s[12:13]
	v_cndmask_b32_e64 v19, 0, v218, s[2:3]
	v_cmp_gt_f32_e64 s[2:3], s82, v16
	v_sub_f32_e32 v15, v15, v19
	v_add_f32_e32 v15, v18, v15
	v_cndmask_b32_e64 v48, 0, 32, s[2:3]
	v_ldexp_f32 v16, v16, v48
	v_log_f32_e32 v16, v16
	v_add_f32_e32 v18, v39, v51
	v_mul_f32_e32 v18, 0xbfb8aa3b, v18
	v_sub_f32_e32 v15, -0.5, v15
	v_mul_f32_e32 v48, 0x3f317217, v16
	v_fma_f32 v48, v16, s83, -v48
	v_fmac_f32_e32 v48, 0x3377d1cf, v16
	v_fmac_f32_e32 v48, 0x3f317217, v16
	v_cmp_lt_f32_e64 s[12:13], |v16|, s84
	v_exp_f32_e32 v18, v18
	v_mul_f32_e32 v15, 0x3fb8aa3b, v15
	v_cndmask_b32_e64 v16, v16, v48, s[12:13]
	v_cndmask_b32_e64 v48, 0, v218, s[2:3]
	v_sub_f32_e32 v16, v16, v48
	v_add_f32_e32 v16, v17, v16
	v_add_f32_e32 v17, v40, v52
	v_mul_f32_e32 v17, 0xbfb8aa3b, v17
	v_exp_f32_e32 v17, v17
	v_sub_f32_e32 v16, -0.5, v16
	v_mul_f32_e32 v16, 0x3fb8aa3b, v16
	v_exp_f32_e32 v15, v15
	v_add_f32_e32 v17, 1.0, v17
	v_rcp_f32_e32 v48, v17
	v_add_f32_e32 v17, v49, v57
	v_max_f32_e64 v40, -v17, 0
	v_mul_f32_e64 v17, |v17|, s81
	v_exp_f32_e32 v17, v17
	v_exp_f32_e32 v16, v16
	v_add_f32_e32 v18, 1.0, v18
	v_rcp_f32_e32 v39, v18
	v_add_f32_e32 v17, 1.0, v17
	v_cmp_gt_f32_e64 s[2:3], s82, v17
	v_mul_f32_e32 v15, 0xbfb8aa3b, v15
	v_mul_f32_e32 v16, 0xbfb8aa3b, v16
	v_cndmask_b32_e64 v49, 0, 32, s[2:3]
	v_ldexp_f32 v17, v17, v49
	v_log_f32_e32 v17, v17
	v_exp_f32_e32 v15, v15
	v_exp_f32_e32 v16, v16
	v_pk_fma_f32 v[26:27], v[58:59], v[26:27], v[110:111]
	v_mul_f32_e32 v49, 0x3f317217, v17
	v_fma_f32 v49, v17, s83, -v49
	v_fmac_f32_e32 v49, 0x3377d1cf, v17
	v_fmac_f32_e32 v49, 0x3f317217, v17
	v_cmp_lt_f32_e64 s[12:13], |v17|, s84
	v_xor_b32_e32 v19, 0x80000000, v47
	v_xor_b32_e32 v18, 0x80000000, v46
	v_cndmask_b32_e64 v17, v17, v49, s[12:13]
	v_cndmask_b32_e64 v49, 0, v218, s[2:3]
	v_sub_f32_e32 v17, v17, v49
	v_add_f32_e32 v17, v40, v17
	v_add_f32_e32 v40, v41, v53
	v_mul_f32_e32 v40, 0xbfb8aa3b, v40
	v_sub_f32_e32 v17, -0.5, v17
	v_exp_f32_e32 v40, v40
	v_mul_f32_e32 v17, 0x3fb8aa3b, v17
	v_exp_f32_e32 v17, v17
	v_or_b32_e32 v100, v100, v119
	v_add_f32_e32 v40, 1.0, v40
	v_rcp_f32_e32 v49, v40
	v_mul_f32_e32 v17, 0xbfb8aa3b, v17
	v_exp_f32_e32 v17, v17
	v_pk_add_f32 v[40:41], v[38:39], -1.0 op_sel_hi:[1,0]
	v_pk_add_f32 v[50:51], v[48:49], -1.0 op_sel_hi:[1,0]
	s_waitcnt vmcnt(1)
	v_pk_fma_f32 v[40:41], v[42:43], v[40:41], 1.0 op_sel_hi:[1,1,0]
	v_pk_fma_f32 v[44:45], v[44:45], v[50:51], 1.0 op_sel_hi:[1,1,0]
	v_pk_mul_f32 v[40:41], v[62:63], v[40:41]
	v_pk_mul_f32 v[42:43], v[20:21], v[44:45]
	global_store_dwordx4 v[22:23], v[14:17], off nt
	v_pk_mul_f32 v[50:51], v[64:65], v[0:1] op_sel_hi:[1,0]
	v_pk_mul_f32 v[44:45], v[38:39], v[46:47]
	v_lshl_add_u64 v[14:15], s[66:67], 0, v[30:31]
	global_store_dwordx4 v[14:15], v[40:43], off nt
	v_lshl_add_u64 v[14:15], s[68:69], 0, v[30:31]
	v_xor_b32_e32 v20, 0x80000000, v50
	v_xor_b32_e32 v21, 0x80000000, v51
	global_store_dwordx4 v[14:15], v[26:29], off nt
	v_lshl_add_u64 v[14:15], s[70:71], 0, v[30:31]
	v_pk_mul_f32 v[46:47], v[48:49], v[50:51]
	global_store_dwordx4 v[14:15], v[18:21], off nt
	v_lshl_add_u64 v[14:15], s[72:73], 0, v[30:31]
	global_store_dwordx4 v[14:15], v[44:47], off nt
	v_lshl_add_u64 v[14:15], s[74:75], 0, v[30:31]
	s_waitcnt lgkmcnt(0)
	global_store_dwordx4 v[14:15], v[34:37], off nt
	global_load_dwordx4 v[18:21], v102, s[34:35] offset:768
	global_load_dwordx4 v[50:53], v104, s[76:77]
	s_nop 0
	global_load_dwordx4 v[14:17], v104, s[78:79]
	global_load_dwordx4 v[34:37], v102, s[36:37] offset:768
	global_load_dwordx4 v[26:29], v102, s[40:41] offset:768
	global_load_dwordx4 v[54:57], v102, s[42:43] offset:768
	global_load_dwordx4 v[22:25], v102, s[52:53] offset:768
	v_sub_f32_e32 v47, v7, v97
	v_sub_f32_e32 v46, v6, v96
	v_sub_f32_e32 v7, v11, v107
	v_sub_f32_e32 v6, v10, v106
	v_sub_f32_e32 v49, v9, v99
	v_sub_f32_e32 v48, v8, v98
	v_sub_f32_e32 v9, v13, v109
	v_sub_f32_e32 v8, v12, v108
	ds_read_b128 v[42:45], v171
	ds_read_b128 v[38:41], v172
	ds_read_b128 v[30:33], v173
	v_sub_f32_e32 v13, v5, v95
	v_sub_f32_e32 v12, v4, v94
	v_sub_f32_e32 v11, v3, v93
	v_sub_f32_e32 v10, v2, v92
	s_waitcnt vmcnt(6)
	v_pk_fma_f32 v[20:21], v[48:49], v[20:21], v[98:99]
	s_waitcnt vmcnt(5)
	v_pk_fma_f32 v[50:51], v[6:7], v[50:51], v[106:107]
	v_pk_fma_f32 v[8:9], v[8:9], v[52:53], v[108:109]
	s_waitcnt vmcnt(4)
	v_pk_fma_f32 v[10:11], v[10:11], v[14:15], v[92:93]
	s_waitcnt vmcnt(2) lgkmcnt(1)
	v_add_f32_e32 v29, v29, v41
	s_waitcnt vmcnt(1)
	v_pk_mul_f32 v[4:5], v[50:51], v[54:55]
	v_pk_mul_f32 v[52:53], v[8:9], v[56:57]
	v_pk_mul_f32 v[2:3], v[4:5], v[4:5]
	v_mul_f32_e32 v29, 0xbfb8aa3b, v29
	v_pk_fma_f32 v[2:3], v[52:53], v[52:53], v[2:3]
	v_exp_f32_e32 v29, v29
	v_add_f32_e32 v0, v2, v3
	v_add_f32_e32 v2, v34, v42
	v_max_f32_e64 v3, -v2, 0
	v_mul_f32_e64 v2, |v2|, s81
	v_exp_f32_e32 v2, v2
	v_add_f32_dpp v0, v0, v0 quad_perm:[1,0,3,2] row_mask:0xf bank_mask:0xf bound_ctrl:1
	v_add_f32_e32 v29, 1.0, v29
	v_rcp_f32_e32 v29, v29
	v_add_f32_e32 v2, 1.0, v2
	v_cmp_gt_f32_e64 s[2:3], s82, v2
	v_add_f32_dpp v0, v0, v0 quad_perm:[2,3,0,1] row_mask:0xf bank_mask:0xf bound_ctrl:1
	v_lshlrev_b64 v[14:15], 2, v[100:101]
	v_cndmask_b32_e64 v6, 0, 32, s[2:3]
	v_ldexp_f32 v2, v2, v6
	v_log_f32_e32 v2, v2
	v_add_f32_dpp v0, v0, v0 row_half_mirror row_mask:0xf bank_mask:0xf bound_ctrl:1
	v_pk_fma_f32 v[18:19], v[46:47], v[18:19], v[96:97]
	v_pk_fma_f32 v[12:13], v[12:13], v[16:17], v[94:95]
	v_mul_f32_e32 v6, 0x3f317217, v2
	v_fma_f32 v6, v2, s83, -v6
	v_fmac_f32_e32 v6, 0x3377d1cf, v2
	v_fmac_f32_e32 v6, 0x3f317217, v2
	v_cmp_lt_f32_e64 s[12:13], |v2|, s84
	v_add_f32_dpp v0, v0, v0 row_ror:8 row_mask:0xf bank_mask:0xf bound_ctrl:1
	v_add_f32_e32 v0, 0x2b8cbccc, v0
	v_cndmask_b32_e64 v2, v2, v6, s[12:13]
	v_cndmask_b32_e64 v6, 0, v218, s[2:3]
	v_sub_f32_e32 v2, v2, v6
	v_add_f32_e32 v2, v3, v2
	v_add_f32_e32 v3, v26, v38
	v_mul_f32_e32 v3, 0xbfb8aa3b, v3
	v_exp_f32_e32 v3, v3
	v_rsq_f32_e32 v0, v0
	v_sub_f32_e32 v2, -0.5, v2
	v_mul_f32_e32 v2, 0x3fb8aa3b, v2
	v_add_f32_e32 v3, 1.0, v3
	v_rcp_f32_e32 v26, v3
	v_add_f32_e32 v3, v35, v43
	v_max_f32_e64 v6, -v3, 0
	v_mul_f32_e64 v3, |v3|, s81
	v_exp_f32_e32 v3, v3
	v_pk_mul_f32 v[34:35], v[4:5], v[0:1] op_sel_hi:[1,0]
	v_add_f32_e32 v4, v36, v44
	v_max_f32_e64 v5, -v4, 0
	v_add_f32_e32 v3, 1.0, v3
	v_cmp_gt_f32_e64 s[2:3], s82, v3
	v_mul_f32_e64 v4, |v4|, s81
	v_exp_f32_e32 v4, v4
	v_cndmask_b32_e64 v7, 0, 32, s[2:3]
	v_ldexp_f32 v3, v3, v7
	v_log_f32_e32 v3, v3
	v_add_f32_e32 v4, 1.0, v4
	v_exp_f32_e32 v2, v2
	v_lshl_add_u64 v[16:17], s[54:55], 0, v[14:15]
	v_mul_f32_e32 v7, 0x3f317217, v3
	v_fma_f32 v7, v3, s83, -v7
	v_fmac_f32_e32 v7, 0x3377d1cf, v3
	v_fmac_f32_e32 v7, 0x3f317217, v3
	v_cmp_lt_f32_e64 s[12:13], |v3|, s84
	v_mul_f32_e32 v2, 0xbfb8aa3b, v2
	v_exp_f32_e32 v2, v2
	v_cndmask_b32_e64 v3, v3, v7, s[12:13]
	v_cndmask_b32_e64 v7, 0, v218, s[2:3]
	v_cmp_gt_f32_e64 s[2:3], s82, v4
	v_sub_f32_e32 v3, v3, v7
	v_add_f32_e32 v3, v6, v3
	v_cndmask_b32_e64 v36, 0, 32, s[2:3]
	v_ldexp_f32 v4, v4, v36
	v_log_f32_e32 v4, v4
	v_add_f32_e32 v6, v27, v39
	v_mul_f32_e32 v6, 0xbfb8aa3b, v6
	v_sub_f32_e32 v3, -0.5, v3
	v_mul_f32_e32 v36, 0x3f317217, v4
	v_fma_f32 v36, v4, s83, -v36
	v_fmac_f32_e32 v36, 0x3377d1cf, v4
	v_fmac_f32_e32 v36, 0x3f317217, v4
	v_cmp_lt_f32_e64 s[12:13], |v4|, s84
	v_exp_f32_e32 v6, v6
	v_mul_f32_e32 v3, 0x3fb8aa3b, v3
	v_cndmask_b32_e64 v4, v4, v36, s[12:13]
	v_cndmask_b32_e64 v36, 0, v218, s[2:3]
	v_sub_f32_e32 v4, v4, v36
	v_add_f32_e32 v4, v5, v4
	v_add_f32_e32 v5, v28, v40
	v_mul_f32_e32 v5, 0xbfb8aa3b, v5
	v_exp_f32_e32 v5, v5
	v_sub_f32_e32 v4, -0.5, v4
	v_mul_f32_e32 v4, 0x3fb8aa3b, v4
	v_exp_f32_e32 v3, v3
	v_add_f32_e32 v5, 1.0, v5
	v_rcp_f32_e32 v28, v5
	v_add_f32_e32 v5, v37, v45
	v_max_f32_e64 v36, -v5, 0
	v_mul_f32_e64 v5, |v5|, s81
	v_exp_f32_e32 v5, v5
	v_exp_f32_e32 v4, v4
	v_add_f32_e32 v6, 1.0, v6
	v_rcp_f32_e32 v27, v6
	v_add_f32_e32 v5, 1.0, v5
	v_cmp_gt_f32_e64 s[2:3], s82, v5
	v_mul_f32_e32 v3, 0xbfb8aa3b, v3
	v_mul_f32_e32 v4, 0xbfb8aa3b, v4
	v_cndmask_b32_e64 v37, 0, 32, s[2:3]
	v_ldexp_f32 v5, v5, v37
	v_log_f32_e32 v5, v5
	v_exp_f32_e32 v3, v3
	v_exp_f32_e32 v4, v4
	v_pk_add_f32 v[38:39], v[28:29], -1.0 op_sel_hi:[1,0]
	v_mul_f32_e32 v37, 0x3f317217, v5
	v_fma_f32 v37, v5, s83, -v37
	v_fmac_f32_e32 v37, 0x3377d1cf, v5
	v_fmac_f32_e32 v37, 0x3f317217, v5
	v_cmp_lt_f32_e64 s[12:13], |v5|, s84
	s_waitcnt vmcnt(0)
	v_pk_fma_f32 v[24:25], v[24:25], v[38:39], 1.0 op_sel_hi:[1,1,0]
	global_store_dwordx4 v[16:17], v[18:21], off nt
	v_cndmask_b32_e64 v5, v5, v37, s[12:13]
	v_cndmask_b32_e64 v37, 0, v218, s[2:3]
	v_sub_f32_e32 v5, v5, v37
	v_add_f32_e32 v5, v36, v5
	v_sub_f32_e32 v5, -0.5, v5
	v_mul_f32_e32 v5, 0x3fb8aa3b, v5
	v_exp_f32_e32 v5, v5
	v_pk_add_f32 v[36:37], v[26:27], -1.0 op_sel_hi:[1,0]
	v_lshl_add_u64 v[16:17], s[56:57], 0, v[14:15]
	v_pk_fma_f32 v[22:23], v[22:23], v[36:37], 1.0 op_sel_hi:[1,1,0]
	v_mul_f32_e32 v5, 0xbfb8aa3b, v5
	v_exp_f32_e32 v5, v5
	v_pk_mul_f32 v[24:25], v[8:9], v[24:25]
	v_pk_mul_f32 v[22:23], v[50:51], v[22:23]
	v_pk_mul_f32 v[36:37], v[52:53], v[0:1] op_sel_hi:[1,0]
	global_store_dwordx4 v[16:17], v[2:5], off nt
	v_xor_b32_e32 v7, 0x80000000, v35
	v_xor_b32_e32 v6, 0x80000000, v34
	v_lshl_add_u64 v[2:3], s[66:67], 0, v[14:15]
	global_store_dwordx4 v[2:3], v[22:25], off nt
	v_lshl_add_u64 v[2:3], s[68:69], 0, v[14:15]
	v_xor_b32_e32 v8, 0x80000000, v36
	v_xor_b32_e32 v9, 0x80000000, v37
	global_store_dwordx4 v[2:3], v[10:13], off nt
	v_lshl_add_u64 v[2:3], s[70:71], 0, v[14:15]
	v_readlane_b32 s2, v252, 50
	v_pk_mul_f32 v[26:27], v[26:27], v[34:35]
	v_pk_mul_f32 v[28:29], v[28:29], v[36:37]
	global_store_dwordx4 v[2:3], v[6:9], off nt
	v_lshl_add_u64 v[2:3], s[72:73], 0, v[14:15]
	s_add_i32 s0, s0, s2
	global_store_dwordx4 v[2:3], v[26:29], off nt
	v_lshl_add_u64 v[2:3], s[74:75], 0, v[14:15]
	s_cmpk_gt_i32 s4, 0x43f
	s_waitcnt lgkmcnt(0)
	global_store_dwordx4 v[2:3], v[30:33], off nt
	s_barrier
	s_cbranch_scc1 .LBB0_1878

.Lgdp_c3_done:
	v_mul_f32_e32 v28, v92, v140
	v_mul_f32_e32 v29, v93, v141
	v_mul_f32_e32 v30, v94, v142
	v_mul_f32_e32 v31, v95, v143
	v_fmac_f32_e32 v28, v104, v152
	v_fmac_f32_e32 v29, v105, v153
	v_fmac_f32_e32 v30, v106, v154
	v_fmac_f32_e32 v31, v107, v155
	v_fmac_f32_e32 v28, v116, v164
	v_fmac_f32_e32 v29, v117, v165
	v_fmac_f32_e32 v30, v118, v166
	v_fmac_f32_e32 v31, v119, v167
	v_fmac_f32_e32 v28, v128, v176
	v_fmac_f32_e32 v29, v129, v177
	v_fmac_f32_e32 v30, v130, v178
	v_fmac_f32_e32 v31, v131, v179
	v_mul_f32_e32 v32, v96, v144
	v_mul_f32_e32 v33, v97, v145
	v_mul_f32_e32 v34, v98, v146
	v_mul_f32_e32 v35, v99, v147
	v_fmac_f32_e32 v32, v108, v156
	v_fmac_f32_e32 v33, v109, v157
	v_fmac_f32_e32 v34, v110, v158
	v_fmac_f32_e32 v35, v111, v159
	v_fmac_f32_e32 v32, v120, v168
	v_fmac_f32_e32 v33, v121, v169
	v_fmac_f32_e32 v34, v122, v170
	v_fmac_f32_e32 v35, v123, v171
	v_fmac_f32_e32 v32, v132, v180
	v_fmac_f32_e32 v33, v133, v181
	v_fmac_f32_e32 v34, v134, v182
	v_fmac_f32_e32 v35, v135, v183
	v_mul_f32_e32 v36, v100, v148
	v_mul_f32_e32 v37, v101, v149
	v_mul_f32_e32 v38, v102, v150
	v_mul_f32_e32 v39, v103, v151
	v_fmac_f32_e32 v36, v112, v160
	v_fmac_f32_e32 v37, v113, v161
	v_fmac_f32_e32 v38, v114, v162
	v_fmac_f32_e32 v39, v115, v163
	v_fmac_f32_e32 v36, v124, v172
	v_fmac_f32_e32 v37, v125, v173
	v_fmac_f32_e32 v38, v126, v174
	v_fmac_f32_e32 v39, v127, v175
	v_fmac_f32_e32 v36, v194, v184
	v_fmac_f32_e32 v37, v195, v185
	v_fmac_f32_e32 v38, v196, v186
	v_fmac_f32_e32 v39, v197, v187
	v_mul_f32_e32 v44, s81, v28
	v_mul_f32_e32 v45, s81, v29
	v_mul_f32_e32 v46, s81, v30
	v_mul_f32_e32 v47, s81, v31
	v_mul_f32_e32 v48, s81, v32
	v_mul_f32_e32 v49, s81, v33
	v_mul_f32_e32 v50, s81, v34
	v_mul_f32_e32 v51, s81, v35
	v_mul_f32_e32 v52, s81, v36
	v_mul_f32_e32 v53, s81, v37
	v_mul_f32_e32 v54, s81, v38
	v_mul_f32_e32 v55, s81, v39
	v_exp_f32_e32 v44, v44
	v_exp_f32_e32 v45, v45
	v_exp_f32_e32 v46, v46
	v_exp_f32_e32 v47, v47
	v_exp_f32_e32 v48, v48
	v_exp_f32_e32 v49, v49
	v_exp_f32_e32 v50, v50
	v_exp_f32_e32 v51, v51
	v_exp_f32_e32 v52, v52
	v_exp_f32_e32 v53, v53
	v_exp_f32_e32 v54, v54
	v_exp_f32_e32 v55, v55
	v_add_f32_e32 v44, 1.0, v44
	v_add_f32_e32 v45, 1.0, v45
	v_add_f32_e32 v46, 1.0, v46
	v_add_f32_e32 v47, 1.0, v47
	v_add_f32_e32 v48, 1.0, v48
	v_add_f32_e32 v49, 1.0, v49
	v_add_f32_e32 v50, 1.0, v50
	v_add_f32_e32 v51, 1.0, v51
	v_add_f32_e32 v52, 1.0, v52
	v_add_f32_e32 v53, 1.0, v53
	v_add_f32_e32 v54, 1.0, v54
	v_add_f32_e32 v55, 1.0, v55
	v_rcp_f32_e32 v44, v44
	v_rcp_f32_e32 v45, v45
	v_rcp_f32_e32 v46, v46
	v_rcp_f32_e32 v47, v47
	v_rcp_f32_e32 v48, v48
	v_rcp_f32_e32 v49, v49
	v_rcp_f32_e32 v50, v50
	v_rcp_f32_e32 v51, v51
	v_rcp_f32_e32 v52, v52
	v_rcp_f32_e32 v53, v53
	v_rcp_f32_e32 v54, v54
	v_rcp_f32_e32 v55, v55
	v_mul_f32_e32 v28, v28, v44
	v_mul_f32_e32 v29, v29, v45
	v_mul_f32_e32 v30, v30, v46
	v_mul_f32_e32 v31, v31, v47
	v_mul_f32_e32 v32, v32, v48
	v_mul_f32_e32 v33, v33, v49
	v_mul_f32_e32 v34, v34, v50
	v_mul_f32_e32 v35, v35, v51
	v_mul_f32_e32 v36, v36, v52
	v_mul_f32_e32 v37, v37, v53
	v_mul_f32_e32 v38, v38, v54
	v_mul_f32_e32 v39, v39, v55
	v_mul_f32_e32 v44, v28, v28
	v_mul_f32_e32 v45, v32, v32
	v_mul_f32_e32 v46, v29, v29
	v_mul_f32_e32 v47, v33, v33
	v_fmac_f32_e32 v44, v30, v30
	v_fmac_f32_e32 v45, v34, v34
	v_fmac_f32_e32 v46, v31, v31
	v_fmac_f32_e32 v47, v35, v35
	v_add_f32_e32 v44, v44, v46
	v_add_f32_e32 v45, v45, v47
	s_nop 0
	v_add_f32_dpp v44, v44, v44 quad_perm:[1,0,3,2] row_mask:0xf bank_mask:0xf bound_ctrl:1
	v_add_f32_dpp v45, v45, v45 quad_perm:[1,0,3,2] row_mask:0xf bank_mask:0xf bound_ctrl:1
	s_nop 0
	v_add_f32_dpp v44, v44, v44 quad_perm:[2,3,0,1] row_mask:0xf bank_mask:0xf bound_ctrl:1
	v_add_f32_dpp v45, v45, v45 quad_perm:[2,3,0,1] row_mask:0xf bank_mask:0xf bound_ctrl:1
	s_nop 0
	v_add_f32_dpp v44, v44, v44 row_half_mirror row_mask:0xf bank_mask:0xf bound_ctrl:1
	v_add_f32_dpp v45, v45, v45 row_half_mirror row_mask:0xf bank_mask:0xf bound_ctrl:1
	s_nop 0
	v_add_f32_dpp v44, v44, v44 row_ror:8 row_mask:0xf bank_mask:0xf bound_ctrl:1
	v_add_f32_dpp v45, v45, v45 row_ror:8 row_mask:0xf bank_mask:0xf bound_ctrl:1
	s_nop 0
	ds_bpermute_b32 v46, v73, v44
	ds_bpermute_b32 v47, v73, v45
	s_add_u32 s26, s4, s44
	s_addc_u32 s27, s5, 0
	s_waitcnt lgkmcnt(0)
	v_add_f32_e32 v44, v44, v46
	v_add_f32_e32 v45, v45, v47
	v_add_f32_e32 v44, 0x2b8cbccc, v44
	v_add_f32_e32 v45, 0x2b8cbccc, v45
	v_rsq_f32_e32 v44, v44
	v_rsq_f32_e32 v45, v45
	s_nop 0
	v_mul_f32_e32 v44, 0x3db504f3, v44
	v_mul_f32_e32 v28, v28, v44
	v_mul_f32_e32 v29, v29, v44
	v_mul_f32_e32 v30, v30, v44
	v_mul_f32_e32 v31, v31, v44
	v_mul_f32_e32 v32, v32, v45
	v_mul_f32_e32 v33, v33, v45
	v_mul_f32_e32 v34, v34, v45
	v_mul_f32_e32 v35, v35, v45
	global_store_dwordx4 v56, v[28:31], s[22:23] nt
	global_store_dwordx4 v56, v[32:35], s[24:25] nt
	global_store_dwordx4 v56, v[36:39], s[28:29] nt
	s_and_saveexec_b64 s[38:39], s[2:3]
	v_lshlrev_b32_e32 v44, 16, v26
	v_lshlrev_b32_e32 v45, 16, v27
	v_mul_f32_e32 v44, s81, v44
	v_add_f32_e32 v45, v189, v45
	v_exp_f32_e32 v44, v44
	v_mul_f32_e64 v46, |v45|, s81
	v_exp_f32_e32 v46, v46
	v_add_f32_e32 v44, 1.0, v44
	v_rcp_f32_e32 v44, v44
	v_max_f32_e32 v45, 0, v45
	v_add_f32_e32 v46, 1.0, v46
	global_store_dword v192, v44, s[26:27]
	v_cmp_gt_f32_e32 vcc, s82, v46
	s_nop 1
	v_cndmask_b32_e64 v47, 0, 32, vcc
	v_ldexp_f32 v46, v46, v47
	v_log_f32_e32 v46, v46
	s_nop 0
	v_mul_f32_e32 v47, 0x3f317217, v46
	v_fma_f32 v47, v46, s83, -v47
	v_fmac_f32_e32 v47, 0x3377d1cf, v46
	v_fmac_f32_e32 v47, 0x3f317217, v46
	v_cmp_lt_f32_e64 s[6:7], |v46|, s84
	s_nop 1
	v_cndmask_b32_e64 v46, v46, v47, s[6:7]
	v_cndmask_b32_e32 v47, 0, v218, vcc
	v_sub_f32_e32 v46, v46, v47
	v_add_f32_e32 v45, v45, v46
	v_mul_f32_e32 v45, v45, v188
	v_mul_f32_e32 v45, s81, v45
	v_exp_f32_e32 v45, v45
	s_nop 0
	global_store_dword v192, v45, s[26:27] offset:4
	s_or_b64 exec, exec, s[38:39]
	s_add_i32 s19, s19, s50
	s_add_i32 s18, s18, s80
	s_cmp_gt_i32 s19, 0x87ff
	s_cbranch_scc0 .LBB0_1881
	s_branch .LBB0_1931

.LBB0_1923:
	s_waitcnt vmcnt(6)
	v_pk_fma_f32 v[10:11], v[10:11], v[14:15], 0 op_sel_hi:[1,1,0]
	v_pk_fma_f32 v[4:5], v[4:5], v[8:9], 0 op_sel_hi:[1,1,0]
	s_waitcnt vmcnt(3)
	v_pk_fma_f32 v[10:11], v[34:35], v[38:39], v[10:11]
	v_pk_fma_f32 v[4:5], v[28:29], v[32:33], v[4:5]
	v_pk_fma_f32 v[12:13], v[12:13], v[16:17], 0 op_sel_hi:[1,1,0]
	s_waitcnt vmcnt(0)
	v_pk_fma_f32 v[16:17], v[62:63], v[66:67], v[10:11]
	v_pk_fma_f32 v[10:11], v[52:53], v[60:61], v[4:5]
	v_pk_fma_f32 v[4:5], v[18:19], v[22:23], 0 op_sel_hi:[1,1,0]
	v_pk_fma_f32 v[2:3], v[2:3], v[6:7], 0 op_sel_hi:[1,1,0]
	v_pk_fma_f32 v[8:9], v[42:43], v[46:47], v[4:5]
	global_load_dwordx4 v[4:7], v76, s[34:35]
	s_add_i32 s6, s26, s27
	s_mul_hi_i32 s7, s6, 0x3c00
	s_mulk_i32 s6, 0x3c00
	v_readlane_b32 s26, v251, 16
	v_readlane_b32 s27, v251, 17
	s_add_u32 s6, s26, s6
	v_pk_fma_f32 v[12:13], v[36:37], v[40:41], v[12:13]
	v_pk_fma_f32 v[2:3], v[26:27], v[30:31], v[2:3]
	s_addc_u32 s7, s27, s7
	v_pk_fma_f32 v[14:15], v[64:65], v[68:69], v[12:13]
	v_pk_fma_f32 v[12:13], v[50:51], v[58:59], v[2:3]
	v_pk_fma_f32 v[2:3], v[20:21], v[24:25], 0 op_sel_hi:[1,1,0]
	s_add_u32 s6, s6, 0x1a00
	v_pk_fma_f32 v[2:3], v[44:45], v[48:49], v[2:3]
	s_addc_u32 s7, s7, 0
	s_ashr_i32 s41, s40, 31
	s_waitcnt vmcnt(0)
	v_pk_fma_f32 v[2:3], v[56:57], v[6:7], v[2:3]
	global_load_dwordx2 v[6:7], v79, s[6:7]
	v_pk_fma_f32 v[4:5], v[54:55], v[4:5], v[8:9]
	s_waitcnt vmcnt(0)
	v_lshlrev_b32_e32 v18, 16, v6
	v_and_b32_e32 v19, 0xffff0000, v6
	v_lshlrev_b32_e32 v20, 16, v7
	v_and_b32_e32 v21, 0xffff0000, v7
	global_load_dwordx4 v[6:9], v77, s[36:37]
	s_waitcnt vmcnt(0)
	v_pk_fma_f32 v[8:9], v[8:9], v[20:21], v[10:11]
	global_load_dwordx2 v[10:11], v80, s[6:7]
	v_pk_fma_f32 v[6:7], v[6:7], v[18:19], v[12:13]
	s_waitcnt vmcnt(0)
	v_lshlrev_b32_e32 v18, 16, v10
	v_and_b32_e32 v19, 0xffff0000, v10
	v_lshlrev_b32_e32 v20, 16, v11
	v_and_b32_e32 v21, 0xffff0000, v11
	global_load_dwordx4 v[10:13], v78, s[36:37]
	s_waitcnt vmcnt(0)
	v_pk_fma_f32 v[12:13], v[12:13], v[20:21], v[14:15]
	global_load_dwordx2 v[14:15], v81, s[6:7]
	v_pk_fma_f32 v[10:11], v[10:11], v[18:19], v[16:17]
	s_lshl_b64 s[6:7], s[40:41], 10
	v_mov_b32_e32 v23, s7
	v_or_b32_e32 v22, s6, v75
	v_lshlrev_b64 v[22:23], 2, v[22:23]
	v_lshl_add_u64 v[24:25], s[22:23], 0, v[22:23]
	s_waitcnt vmcnt(0)
	v_lshlrev_b32_e32 v18, 16, v14
	v_and_b32_e32 v19, 0xffff0000, v14
	v_lshlrev_b32_e32 v20, 16, v15
	v_and_b32_e32 v21, 0xffff0000, v15
	global_load_dwordx4 v[14:17], v76, s[36:37]
	s_waitcnt vmcnt(0)
	v_pk_fma_f32 v[4:5], v[14:15], v[18:19], v[4:5]
	v_mul_f32_e32 v14, 0xbfb8aa3b, v6
	v_mul_f32_e32 v15, 0xbfb8aa3b, v7
	v_exp_f32_e32 v14, v14
	v_exp_f32_e32 v15, v15
	v_pk_fma_f32 v[2:3], v[16:17], v[20:21], v[2:3]
	v_add_f32_e32 v14, 1.0, v14
	v_add_f32_e32 v15, 1.0, v15
	v_rcp_f32_e32 v14, v14
	v_rcp_f32_e32 v15, v15
	v_mul_f32_e32 v16, 0xbfb8aa3b, v2
	v_mul_f32_e32 v17, 0xbfb8aa3b, v3
	v_exp_f32_e32 v16, v16
	v_pk_mul_f32 v[6:7], v[6:7], v[14:15]
	v_mul_f32_e32 v14, 0xbfb8aa3b, v8
	v_mul_f32_e32 v15, 0xbfb8aa3b, v9
	v_exp_f32_e32 v14, v14
	v_exp_f32_e32 v15, v15
	v_mul_f32_e32 v21, v7, v7
	v_mul_f32_e32 v20, v6, v6
	v_add_f32_e32 v14, 1.0, v14
	v_add_f32_e32 v15, 1.0, v15
	v_rcp_f32_e32 v14, v14
	v_rcp_f32_e32 v15, v15
	v_exp_f32_e32 v17, v17
	v_add_f32_e32 v16, 1.0, v16
	v_rcp_f32_e32 v16, v16
	v_pk_mul_f32 v[8:9], v[8:9], v[14:15]
	v_mul_f32_e32 v14, 0xbfb8aa3b, v10
	v_mul_f32_e32 v15, 0xbfb8aa3b, v11
	v_exp_f32_e32 v14, v14
	v_exp_f32_e32 v15, v15
	v_pk_fma_f32 v[20:21], v[8:9], v[8:9], v[20:21]
	v_add_f32_e32 v17, 1.0, v17
	v_add_f32_e32 v14, 1.0, v14
	v_add_f32_e32 v15, 1.0, v15
	v_rcp_f32_e32 v14, v14
	v_rcp_f32_e32 v15, v15
	v_add_f32_e32 v20, v20, v21
	v_rcp_f32_e32 v17, v17
	v_pk_mul_f32 v[10:11], v[10:11], v[14:15]
	v_mul_f32_e32 v14, 0xbfb8aa3b, v12
	v_mul_f32_e32 v15, 0xbfb8aa3b, v13
	v_exp_f32_e32 v14, v14
	v_exp_f32_e32 v15, v15
	v_add_f32_dpp v20, v20, v20 quad_perm:[1,0,3,2] row_mask:0xf bank_mask:0xf bound_ctrl:1
	v_mul_f32_e32 v19, v11, v11
	v_add_f32_e32 v14, 1.0, v14
	v_add_f32_e32 v15, 1.0, v15
	v_rcp_f32_e32 v14, v14
	v_rcp_f32_e32 v15, v15
	v_add_f32_dpp v20, v20, v20 quad_perm:[2,3,0,1] row_mask:0xf bank_mask:0xf bound_ctrl:1
	v_mul_f32_e32 v18, v10, v10
	v_pk_mul_f32 v[12:13], v[12:13], v[14:15]
	v_add_f32_dpp v20, v20, v20 row_half_mirror row_mask:0xf bank_mask:0xf bound_ctrl:1
	v_pk_fma_f32 v[18:19], v[12:13], v[12:13], v[18:19]
	v_mul_f32_e32 v14, 0xbfb8aa3b, v4
	v_add_f32_dpp v20, v20, v20 row_ror:8 row_mask:0xf bank_mask:0xf bound_ctrl:1
	v_add_f32_e32 v18, v18, v19
	ds_bpermute_b32 v19, v73, v20
	v_mul_f32_e32 v15, 0xbfb8aa3b, v5
	v_add_f32_dpp v18, v18, v18 quad_perm:[1,0,3,2] row_mask:0xf bank_mask:0xf bound_ctrl:1
	v_exp_f32_e32 v14, v14
	v_exp_f32_e32 v15, v15
	v_add_f32_dpp v18, v18, v18 quad_perm:[2,3,0,1] row_mask:0xf bank_mask:0xf bound_ctrl:1
	s_waitcnt lgkmcnt(0)
	v_add_f32_e32 v19, v20, v19
	v_add_f32_e32 v14, 1.0, v14
	v_add_f32_dpp v18, v18, v18 row_half_mirror row_mask:0xf bank_mask:0xf bound_ctrl:1
	v_add_f32_e32 v15, 1.0, v15
	v_rcp_f32_e32 v14, v14
	v_add_f32_dpp v18, v18, v18 row_ror:8 row_mask:0xf bank_mask:0xf bound_ctrl:1
	ds_bpermute_b32 v20, v73, v18
	v_rcp_f32_e32 v15, v15
	s_waitcnt lgkmcnt(0)
	v_add_f32_e32 v20, v18, v20
	v_add_f32_e32 v18, 0x2b8cbccc, v19
	v_rsq_f32_e32 v18, v18
	v_add_f32_e32 v19, 0x2b8cbccc, v20
	v_rsq_f32_e32 v20, v19
	v_pk_mul_f32 v[4:5], v[4:5], v[14:15]
	v_mul_f32_e32 v18, 0x3db504f3, v18
	v_pk_mul_f32 v[8:9], v[8:9], v[18:19] op_sel_hi:[1,0]
	v_pk_mul_f32 v[6:7], v[6:7], v[18:19] op_sel_hi:[1,0]
	global_store_dwordx4 v[24:25], v[6:9], off nt
	v_lshl_add_u64 v[18:19], s[24:25], 0, v[22:23]
	s_nop 0
	v_pk_mul_f32 v[8:9], v[12:13], v[20:21] op_sel_hi:[1,0]
	v_pk_mul_f32 v[6:7], v[10:11], v[20:21] op_sel_hi:[1,0]
	global_store_dwordx4 v[18:19], v[6:9], off nt
	s_nop 1
	v_lshl_add_u64 v[8:9], s[28:29], 0, v[22:23]
	v_pk_mul_f32 v[6:7], v[2:3], v[16:17]
	global_store_dwordx4 v[8:9], v[4:7], off nt
	s_and_saveexec_b64 s[38:39], s[2:3]
	s_cbranch_execz .LBB0_1880
	s_mul_hi_i32 s27, s40, 0x3c00
	s_mul_i32 s26, s40, 0x3c00
	v_readlane_b32 s40, v251, 16
	v_readlane_b32 s41, v251, 17
	s_add_u32 s26, s40, s26
	s_addc_u32 s27, s41, s27
	v_lshlrev_b32_e32 v2, 1, v74
	v_mov_b32_e32 v3, v1
	v_lshl_add_u64 v[2:3], s[26:27], 0, v[2:3]
	v_add_co_u32_e32 v2, vcc, 0x3000, v2
	s_lshl_b64 s[6:7], s[6:7], 2
	s_nop 0
	v_addc_co_u32_e32 v3, vcc, 0, v3, vcc
	global_load_ushort v4, v[2:3], off offset:2560
	s_nop 0
	global_load_ushort v2, v[2:3], off offset:2576
	s_add_u32 s26, s4, s6
	s_addc_u32 s27, s5, s7
	v_lshlrev_b32_e32 v5, 2, v74
	s_waitcnt vmcnt(1)
	v_lshlrev_b32_e32 v3, 16, v4
	v_mul_f32_e32 v3, 0xbfb8aa3b, v3
	v_exp_f32_e32 v3, v3
	v_lshlrev_b32_e32 v4, 3, v74
	s_waitcnt vmcnt(0)
	v_lshlrev_b32_e32 v2, 16, v2
	v_add_f32_e32 v3, 1.0, v3
	v_rcp_f32_e32 v3, v3
	global_store_dword v4, v3, s[26:27]
	global_load_dword v3, v5, s[16:17]
	s_nop 0
	global_load_dword v5, v5, s[12:13]
	s_waitcnt vmcnt(1)
	v_add_f32_e32 v2, v3, v2
	v_mul_f32_e64 v3, |v2|, s81
	v_exp_f32_e32 v3, v3
	s_waitcnt vmcnt(0)
	v_mul_f32_e32 v5, 0x3fb8aa3b, v5
	v_exp_f32_e32 v5, v5
	v_max_f32_e32 v2, 0, v2
	v_add_f32_e32 v3, 1.0, v3
	v_cmp_gt_f32_e32 vcc, s82, v3
	s_nop 1
	v_cndmask_b32_e64 v6, 0, 32, vcc
	v_ldexp_f32 v3, v3, v6
	v_log_f32_e32 v3, v3
	s_nop 0
	v_mul_f32_e32 v6, 0x3f317217, v3
	v_fma_f32 v6, v3, s83, -v6
	v_fmac_f32_e32 v6, 0x3377d1cf, v3
	v_fmac_f32_e32 v6, 0x3f317217, v3
	v_cmp_lt_f32_e64 s[6:7], |v3|, s84
	s_nop 1
	v_cndmask_b32_e64 v3, v3, v6, s[6:7]
	v_cndmask_b32_e32 v6, 0, v218, vcc
	v_sub_f32_e32 v3, v3, v6
	v_add_f32_e32 v2, v2, v3
	v_mul_f32_e32 v2, v2, v5
	v_mul_f32_e32 v2, 0xbfb8aa3b, v2
	v_exp_f32_e32 v2, v2
	global_store_dword v4, v2, s[26:27] offset:4
	s_branch .LBB0_1880

.Lpc_12:
	s_waitcnt vmcnt(11)
	v_lshlrev_b32_e32 v10, 16, v140
	v_and_b32_e32 v11, 0xffff0000, v140
	v_lshlrev_b32_e32 v12, 16, v141
	v_and_b32_e32 v13, 0xffff0000, v141
	global_store_dwordx4 v[8:9], v[10:13], off nt
	s_waitcnt vmcnt(11)
	v_lshlrev_b32_e32 v174, 16, v142
	v_and_b32_e32 v175, 0xffff0000, v142
	v_lshlrev_b32_e32 v176, 16, v143
	v_and_b32_e32 v177, 0xffff0000, v143
	global_store_dwordx4 v[8:9], v[174:177], off offset:1024 nt
	s_waitcnt vmcnt(11)
	v_lshlrev_b32_e32 v10, 16, v144
	v_and_b32_e32 v11, 0xffff0000, v144
	v_lshlrev_b32_e32 v12, 16, v145
	v_and_b32_e32 v13, 0xffff0000, v145
	global_store_dwordx4 v[8:9], v[10:13], off offset:2048 nt
	s_waitcnt vmcnt(11)
	v_lshlrev_b32_e32 v174, 16, v146
	v_and_b32_e32 v175, 0xffff0000, v146
	v_lshlrev_b32_e32 v176, 16, v147
	v_and_b32_e32 v177, 0xffff0000, v147
	global_store_dwordx4 v[8:9], v[174:177], off offset:3072 nt
	s_waitcnt vmcnt(11)
	v_lshlrev_b32_e32 v10, 16, v148
	v_and_b32_e32 v11, 0xffff0000, v148
	v_lshlrev_b32_e32 v12, 16, v149
	v_and_b32_e32 v13, 0xffff0000, v149
	global_store_dwordx4 v[168:169], v[10:13], off nt
	s_waitcnt vmcnt(11)
	v_lshlrev_b32_e32 v174, 16, v150
	v_and_b32_e32 v175, 0xffff0000, v150
	v_lshlrev_b32_e32 v176, 16, v151
	v_and_b32_e32 v177, 0xffff0000, v151
	global_store_dwordx4 v[168:169], v[174:177], off offset:1024 nt
	s_waitcnt vmcnt(11)
	v_lshlrev_b32_e32 v10, 16, v152
	v_and_b32_e32 v11, 0xffff0000, v152
	v_lshlrev_b32_e32 v12, 16, v153
	v_and_b32_e32 v13, 0xffff0000, v153
	global_store_dwordx4 v[168:169], v[10:13], off offset:2048 nt
	s_waitcnt vmcnt(11)
	v_lshlrev_b32_e32 v174, 16, v154
	v_and_b32_e32 v175, 0xffff0000, v154
	v_lshlrev_b32_e32 v176, 16, v155
	v_and_b32_e32 v177, 0xffff0000, v155
	global_store_dwordx4 v[168:169], v[174:177], off offset:3072 nt
	s_waitcnt vmcnt(11)
	v_lshlrev_b32_e32 v10, 16, v156
	v_and_b32_e32 v11, 0xffff0000, v156
	v_lshlrev_b32_e32 v12, 16, v157
	v_and_b32_e32 v13, 0xffff0000, v157
	global_store_dwordx4 v[170:171], v[10:13], off nt
	s_waitcnt vmcnt(11)
	v_lshlrev_b32_e32 v174, 16, v158
	v_and_b32_e32 v175, 0xffff0000, v158
	v_lshlrev_b32_e32 v176, 16, v159
	v_and_b32_e32 v177, 0xffff0000, v159
	global_store_dwordx4 v[170:171], v[174:177], off offset:1024 nt
	s_waitcnt vmcnt(11)
	v_lshlrev_b32_e32 v10, 16, v160
	v_and_b32_e32 v11, 0xffff0000, v160
	v_lshlrev_b32_e32 v12, 16, v161
	v_and_b32_e32 v13, 0xffff0000, v161
	global_store_dwordx4 v[170:171], v[10:13], off offset:2048 nt
	s_waitcnt vmcnt(11)
	v_lshlrev_b32_e32 v174, 16, v162
	v_and_b32_e32 v175, 0xffff0000, v162
	v_lshlrev_b32_e32 v176, 16, v163
	v_and_b32_e32 v177, 0xffff0000, v163
	global_store_dwordx4 v[170:171], v[174:177], off offset:3072 nt
	s_cmpk_lt_u32 s12, 0x340
	s_cbranch_scc1 .Lpc_done
	s_waitcnt vmcnt(12)
	v_lshlrev_b32_e32 v10, 16, v164
	v_and_b32_e32 v11, 0xffff0000, v164
	v_lshlrev_b32_e32 v12, 16, v165
	v_and_b32_e32 v13, 0xffff0000, v165
	global_store_dwordx4 v[172:173], v[10:13], off nt
